# RG-LRU scan units dealt to workgroups in XCD order: all 32 channel groups of a batch on one XCD so their 16-byte row pieces merge in that L2
# speedup vs baseline: 1.0081x; 1.0081x over previous
; #define LAS __attribute__((address_space(3)))
; __global__ void __launch_bounds__(512, 2) mk_fwd(Args args) {
;     ...
;         float* cs = (float*)(ws + WS_ROPE); float* sn = cs + SEQ * 16; float* cdec = sn + SEQ * 16;
;         float* ssq1 = (float*)(ws + WS_SSQ); float* ssq2 = ssq1 + TOK * 16; float* lssq = (float*)(ws + WS_LSSQ);
;         bf16_t* Wb = (bf16_t*)(ws + WS_W);
;         bf16_t* Hb = (bf16_t*)X;
;         bf16_t* CAT = (bf16_t*)X + (size_t)TOK * DM;
;         bf16_t* HbAlt = (bf16_t*)(ws + WS_K);
;         bf16_t* UCONV = (bf16_t*)(ws + WS_A + 48 * MiB);
;         bf16_t* MG = (bf16_t*)(ws + WS_A);
;         bf16_t* GT = (bf16_t*)(ws + WS_GATES); bf16_t* PA = (bf16_t*)(ws + WS_PROJA);
;         bf16_t* Qb = (bf16_t*)(ws + WS_A);
;         bf16_t* HID = (bf16_t*)(ws + WS_HID);
;         bf16_t* Kb = (bf16_t*)(ws + WS_K); bf16_t* Vt = (bf16_t*)(ws + WS_VT); bf16_t* PM = (bf16_t*)(ws + WS_PM); bf16_t* LAb = (bf16_t*)(ws + WS_LA); bf16_t* LBb = (bf16_t*)(ws + WS_LB);
;     ...
;             for (int u = bx; u < 256; u += G) scan_unit(u, LAb, LBb, CAT + 768, (LAS float*)lds);
.LBB0_303:
	s_andn2_b64 vcc, exec, s[0:1]
	s_cbranch_vccnz .LBB0_798
	s_add_u32 s54, s50, 0x100000
	s_addc_u32 s55, s51, 0
	s_add_u32 s58, s50, 0x140000
	s_addc_u32 s59, s51, 0
	s_add_u32 s80, s50, 0x180000
	s_addc_u32 s81, s51, 0
	s_add_u32 s56, s50, 0x1f400000
	s_addc_u32 s57, s51, 0
	s_add_u32 s4, s50, 0x5000000
	s_addc_u32 s5, s51, 0
	s_cmp_lt_i32 s18, 3
	s_mov_b64 s[0:1], -1
	s_cbranch_scc1 .LBB0_559
	s_add_u32 s88, s50, 0x1a000000
	s_addc_u32 s89, s51, 0
	s_add_u32 s84, s50, 0x1d000000
	s_addc_u32 s85, s51, 0
	s_add_u32 s86, s50, 0x1e000000
	s_addc_u32 s87, s51, 0
	s_cmp_gt_i32 s18, 3
	s_cbranch_scc0 .LBB0_358
	s_cmpk_gt_i32 s45, 0xff
	s_cbranch_scc1 .LBB0_313
	s_add_u32 s20, s28, 0x4000600
	s_addc_u32 s21, s29, 0
	s_mov_b32 s24, s45
	s_branch .LBB0_309
